# pec prologue reduction spread over 4 workgroups x 8 waves (was 4 waves of one WG, 128 serial round trips)
# speedup vs baseline: 1.0006x; 1.0006x over previous
; #define KIN(i) (((const float* const*)__builtin_amdgcn_kernarg_segment_ptr())[(i)])
; __device__ __forceinline__ void prologue_phi(bf16* phit, float* pec, int tid, int gtid, int NGT) {
;     ...
;     if (blockIdx.x == 2 % gridDim.x && tid < 256) { const int which = tid >> 6, e = tid & 63;
;         const float* phi = KIN(26 + (which & 1)) + (size_t)(which >> 1) * 131072 + e; const float* pe = KIN(24 + (which & 1)) + (size_t)(which >> 1) * 2048; float sacc = 0.f;
;         for (int k = 0; k < 2048; ++k) sacc += pe[k] * phi[(size_t)k * 64];
;         pec[which * 64 + e] = sacc; }
.LBB0_24:
	s_or_b64 exec, exec, s[0:1]
	s_add_u32 s0, s48, 0x700000
	s_addc_u32 s1, s49, 0
	v_writelane_b32 v252, s0, 5
	s_waitcnt lgkmcnt(0)
	v_writelane_b32 v252, s1, 6
	s_sub_u32 s4, s2, 2
	s_cmp_lt_u32 s4, 4
	s_cselect_b64 s[0:1], -1, 0
	s_cbranch_scc0 .LBB0_28
	s_and_b32 s5, s4, 1
	s_lshl_b32 s5, s5, 3
	s_add_u32 s8, s56, s5
	s_addc_u32 s9, s57, 0
	s_load_dwordx2 s[6:7], s[8:9], 0xc0
	s_load_dwordx2 s[12:13], s[8:9], 0xd0
	s_lshr_b32 s14, s4, 1
	v_readfirstlane_b32 s15, v0
	s_lshr_b32 s15, s15, 6
	v_and_b32_e32 v1, 63, v0
	v_lshrrev_b32_e32 v3, 4, v1
	v_and_b32_e32 v4, 15, v1
	s_lshl_b32 s16, s15, 8
	v_add_u32_e32 v5, s16, v3
	v_lshlrev_b32_e32 v6, 8, v5
	v_lshl_add_u32 v6, v4, 4, v6
	s_lshl_b32 s16, s14, 19
	v_add_u32_e32 v6, s16, v6
	v_add_u32_e32 v8, 0x1000, v6
	v_add_u32_e32 v9, 0x3000, v6
	v_lshlrev_b32_e32 v7, 2, v5
	s_lshl_b32 s16, s14, 13
	v_add_u32_e32 v7, s16, v7
	v_mov_b32_e32 v100, 0
	v_mov_b32_e32 v101, 0
	v_mov_b32_e32 v102, 0
	v_mov_b32_e32 v103, 0
	s_mov_b32 s16, 4
	s_waitcnt lgkmcnt(0)
; __device__ __forceinline__ float siluf(float x) { return x * __builtin_amdgcn_rcpf(1.0f + __expf(-x)); }
; #define KIN(i) (((const float* const*)__builtin_amdgcn_kernarg_segment_ptr())[(i)])
; #define KWS() (((unsigned char* const*)__builtin_amdgcn_kernarg_segment_ptr())[32])
; __device__ __forceinline__ void prologue_mod(const Args& a, LAS unsigned char* lds, int tid, int G) {
;     ...
;     const float* c = KIN(1); const float* ada_w = KIN(2); const float* ada_b = KIN(3);
;     float* mod = (float*)(KWS() + WS_MOD);
;     for (int i = tid; i < BATCH * D; i += 512) { const int b = i / D, k = i - b * D; cact[k * 8 + b] = siluf(c[i]); }
; __device__ __forceinline__ void prologue_phi(bf16* phit, float* pec, int tid, int gtid, int NGT) {
;     ...
;     if (blockIdx.x == 2 % gridDim.x && tid < 256) { const int which = tid >> 6, e = tid & 63;
;         const float* phi = KIN(26 + (which & 1)) + (size_t)(which >> 1) * 131072 + e; const float* pe = KIN(24 + (which & 1)) + (size_t)(which >> 1) * 2048; float sacc = 0.f;
;         for (int k = 0; k < 2048; ++k) sacc += pe[k] * phi[(size_t)k * 64];
;         pec[which * 64 + e] = sacc; }
.Lpec_loop:
	global_load_dword v12, v7, s[6:7]
	global_load_dword v13, v7, s[6:7] offset:16
	global_load_dword v14, v7, s[6:7] offset:32
	global_load_dword v15, v7, s[6:7] offset:48
	global_load_dword v16, v7, s[6:7] offset:64
	global_load_dword v17, v7, s[6:7] offset:80
	global_load_dword v18, v7, s[6:7] offset:96
	global_load_dword v19, v7, s[6:7] offset:112
	global_load_dword v20, v7, s[6:7] offset:128
	global_load_dword v21, v7, s[6:7] offset:144
	global_load_dword v22, v7, s[6:7] offset:160
	global_load_dword v23, v7, s[6:7] offset:176
	global_load_dword v24, v7, s[6:7] offset:192
	global_load_dword v25, v7, s[6:7] offset:208
	global_load_dword v26, v7, s[6:7] offset:224
	global_load_dword v27, v7, s[6:7] offset:240
	global_load_dwordx4 v[28:31], v8, s[12:13] offset:-4096
	global_load_dwordx4 v[32:35], v8, s[12:13] offset:-3072
	global_load_dwordx4 v[36:39], v8, s[12:13] offset:-2048
	global_load_dwordx4 v[40:43], v8, s[12:13] offset:-1024
	global_load_dwordx4 v[44:47], v8, s[12:13]
	global_load_dwordx4 v[48:51], v8, s[12:13] offset:1024
	global_load_dwordx4 v[52:55], v8, s[12:13] offset:2048
	global_load_dwordx4 v[56:59], v8, s[12:13] offset:3072
	global_load_dwordx4 v[60:63], v9, s[12:13] offset:-4096
	global_load_dwordx4 v[64:67], v9, s[12:13] offset:-3072
	global_load_dwordx4 v[68:71], v9, s[12:13] offset:-2048
	global_load_dwordx4 v[72:75], v9, s[12:13] offset:-1024
	global_load_dwordx4 v[76:79], v9, s[12:13]
	global_load_dwordx4 v[80:83], v9, s[12:13] offset:1024
	global_load_dwordx4 v[84:87], v9, s[12:13] offset:2048
	global_load_dwordx4 v[88:91], v9, s[12:13] offset:3072
	s_add_i32 s16, s16, -1
	v_add_u32_e32 v7, 0x100, v7
	v_add_u32_e32 v8, 0x4000, v8
	v_add_u32_e32 v9, 0x4000, v9
	s_waitcnt vmcnt(15)
	v_fmac_f32_e32 v100, v12, v28
	v_fmac_f32_e32 v101, v12, v29
	v_fmac_f32_e32 v102, v12, v30
	v_fmac_f32_e32 v103, v12, v31
	s_waitcnt vmcnt(14)
	v_fmac_f32_e32 v100, v13, v32
	v_fmac_f32_e32 v101, v13, v33
	v_fmac_f32_e32 v102, v13, v34
	v_fmac_f32_e32 v103, v13, v35
	s_waitcnt vmcnt(13)
	v_fmac_f32_e32 v100, v14, v36
	v_fmac_f32_e32 v101, v14, v37
	v_fmac_f32_e32 v102, v14, v38
	v_fmac_f32_e32 v103, v14, v39
	s_waitcnt vmcnt(12)
	v_fmac_f32_e32 v100, v15, v40
	v_fmac_f32_e32 v101, v15, v41
	v_fmac_f32_e32 v102, v15, v42
	v_fmac_f32_e32 v103, v15, v43
	s_waitcnt vmcnt(11)
	v_fmac_f32_e32 v100, v16, v44
	v_fmac_f32_e32 v101, v16, v45
	v_fmac_f32_e32 v102, v16, v46
	v_fmac_f32_e32 v103, v16, v47
	s_waitcnt vmcnt(10)
	v_fmac_f32_e32 v100, v17, v48
	v_fmac_f32_e32 v101, v17, v49
	v_fmac_f32_e32 v102, v17, v50
	v_fmac_f32_e32 v103, v17, v51
	s_waitcnt vmcnt(9)
	v_fmac_f32_e32 v100, v18, v52
	v_fmac_f32_e32 v101, v18, v53
	v_fmac_f32_e32 v102, v18, v54
	v_fmac_f32_e32 v103, v18, v55
	s_waitcnt vmcnt(8)
	v_fmac_f32_e32 v100, v19, v56
	v_fmac_f32_e32 v101, v19, v57
	v_fmac_f32_e32 v102, v19, v58
	v_fmac_f32_e32 v103, v19, v59
	s_waitcnt vmcnt(7)
	v_fmac_f32_e32 v100, v20, v60
	v_fmac_f32_e32 v101, v20, v61
	v_fmac_f32_e32 v102, v20, v62
	v_fmac_f32_e32 v103, v20, v63
	s_waitcnt vmcnt(6)
	v_fmac_f32_e32 v100, v21, v64
	v_fmac_f32_e32 v101, v21, v65
	v_fmac_f32_e32 v102, v21, v66
	v_fmac_f32_e32 v103, v21, v67
	s_waitcnt vmcnt(5)
	v_fmac_f32_e32 v100, v22, v68
	v_fmac_f32_e32 v101, v22, v69
	v_fmac_f32_e32 v102, v22, v70
	v_fmac_f32_e32 v103, v22, v71
	s_waitcnt vmcnt(4)
	v_fmac_f32_e32 v100, v23, v72
	v_fmac_f32_e32 v101, v23, v73
	v_fmac_f32_e32 v102, v23, v74
	v_fmac_f32_e32 v103, v23, v75
	s_waitcnt vmcnt(3)
	v_fmac_f32_e32 v100, v24, v76
	v_fmac_f32_e32 v101, v24, v77
	v_fmac_f32_e32 v102, v24, v78
	v_fmac_f32_e32 v103, v24, v79
	s_waitcnt vmcnt(2)
	v_fmac_f32_e32 v100, v25, v80
	v_fmac_f32_e32 v101, v25, v81
	v_fmac_f32_e32 v102, v25, v82
	v_fmac_f32_e32 v103, v25, v83
	s_waitcnt vmcnt(1)
	v_fmac_f32_e32 v100, v26, v84
	v_fmac_f32_e32 v101, v26, v85
	v_fmac_f32_e32 v102, v26, v86
	v_fmac_f32_e32 v103, v26, v87
	s_waitcnt vmcnt(0)
	v_fmac_f32_e32 v100, v27, v88
	v_fmac_f32_e32 v101, v27, v89
	v_fmac_f32_e32 v102, v27, v90
	v_fmac_f32_e32 v103, v27, v91
	s_cmp_lg_u32 s16, 0
	s_cbranch_scc1 .Lpec_loop
	v_lshlrev_b32_e32 v5, 4, v0
	v_add_u32_e32 v5, 0x10000, v5
	ds_write_b128 v5, v[100:103]
	s_waitcnt lgkmcnt(0)
	s_barrier
	s_cmp_lg_u32 s15, 0
	s_cbranch_scc1 .Lpec_done
	v_lshlrev_b32_e32 v5, 2, v0
	v_add_u32_e32 v5, 0x10000, v5
	ds_read_b32 v12, v5
	ds_read_b32 v13, v5 offset:256
	ds_read_b32 v14, v5 offset:512
	ds_read_b32 v15, v5 offset:768
	ds_read_b32 v16, v5 offset:1024
	ds_read_b32 v17, v5 offset:1280
	ds_read_b32 v18, v5 offset:1536
	ds_read_b32 v19, v5 offset:1792
	ds_read_b32 v20, v5 offset:2048
	ds_read_b32 v21, v5 offset:2304
	ds_read_b32 v22, v5 offset:2560
	ds_read_b32 v23, v5 offset:2816
	ds_read_b32 v24, v5 offset:3072
	ds_read_b32 v25, v5 offset:3328
	ds_read_b32 v26, v5 offset:3584
	ds_read_b32 v27, v5 offset:3840
	ds_read_b32 v28, v5 offset:4096
	ds_read_b32 v29, v5 offset:4352
	ds_read_b32 v30, v5 offset:4608
	ds_read_b32 v31, v5 offset:4864
	ds_read_b32 v32, v5 offset:5120
	ds_read_b32 v33, v5 offset:5376
	ds_read_b32 v34, v5 offset:5632
	ds_read_b32 v35, v5 offset:5888
	ds_read_b32 v36, v5 offset:6144
	ds_read_b32 v37, v5 offset:6400
	ds_read_b32 v38, v5 offset:6656
	ds_read_b32 v39, v5 offset:6912
	ds_read_b32 v40, v5 offset:7168
	ds_read_b32 v41, v5 offset:7424
	ds_read_b32 v42, v5 offset:7680
	ds_read_b32 v43, v5 offset:7936
	s_waitcnt lgkmcnt(0)
	v_add_f32_e32 v12, v12, v13
	v_add_f32_e32 v12, v12, v14
	v_add_f32_e32 v12, v12, v15
	v_add_f32_e32 v12, v12, v16
	v_add_f32_e32 v12, v12, v17
	v_add_f32_e32 v12, v12, v18
	v_add_f32_e32 v12, v12, v19
	v_add_f32_e32 v12, v12, v20
	v_add_f32_e32 v12, v12, v21
	v_add_f32_e32 v12, v12, v22
	v_add_f32_e32 v12, v12, v23
	v_add_f32_e32 v12, v12, v24
	v_add_f32_e32 v12, v12, v25
	v_add_f32_e32 v12, v12, v26
	v_add_f32_e32 v12, v12, v27
	v_add_f32_e32 v12, v12, v28
	v_add_f32_e32 v12, v12, v29
	v_add_f32_e32 v12, v12, v30
	v_add_f32_e32 v12, v12, v31
	v_add_f32_e32 v12, v12, v32
	v_add_f32_e32 v12, v12, v33
	v_add_f32_e32 v12, v12, v34
	v_add_f32_e32 v12, v12, v35
	v_add_f32_e32 v12, v12, v36
	v_add_f32_e32 v12, v12, v37
	v_add_f32_e32 v12, v12, v38
	v_add_f32_e32 v12, v12, v39
	v_add_f32_e32 v12, v12, v40
	v_add_f32_e32 v12, v12, v41
	v_add_f32_e32 v12, v12, v42
	v_add_f32_e32 v12, v12, v43
	s_lshl_b32 s16, s4, 8
	v_lshl_add_u32 v5, v0, 2, s16
	s_add_u32 s8, s48, 0x700000
	s_addc_u32 s9, s49, 0
	global_store_dword v5, v12, s[8:9]
.Lpec_done:
.LBB0_28:
	s_or_b64 exec, exec, s[0:1]
	v_mov_b32_e32 v46, v0
	s_load_dwordx4 s[12:15], s[56:57], 0x8
	s_load_dwordx2 s[0:1], s[56:57], 0x18
	s_movk_i32 s4, 0x4000
	v_cmp_gt_i32_e32 vcc, s4, v46
	s_and_saveexec_b64 s[4:5], vcc
	s_cbranch_execz .LBB0_31
	s_waitcnt lgkmcnt(0)
	v_mov_b32_e32 v2, s12
	v_mov_b32_e32 v3, s13
	v_ashrrev_i32_e32 v47, 31, v46
	v_lshl_add_u32 v1, v46, 5, 0
	v_lshl_add_u64 v[2:3], v[46:47], 2, v[2:3]
	s_mov_b64 s[6:7], 0
	s_mov_b32 s10, 0xffff0004
	s_mov_b64 s[8:9], 0x800
	s_movk_i32 s11, 0x3dff
	v_mov_b32_e32 v4, v46
